# baseline (speedup 1.0000x reference)
; #define PH(k) if (((PHMASK >> (k)) & 1) && P.ph_lo <= (k) && (k) < P.ph_hi)
; #define SYNC(k) do { if ((k) + 1 < P.ph_hi) { if ((k) == 0) grid.sync(); else xcd_barrier(xb); } } while (0)
; #define REP(b) for (int _rep = 0; _rep < (((REPMASK >> (b)) & 1) ? 2 : 1); ++_rep)
; __device__ void phase_na(const Params& P, unsigned char* smem) {
;     const int tid = threadIdx.x, lane = tid & 63, wid = tid >> 6, l15 = lane & 15, l4 = lane >> 4;
;     float* rpb_s = (float*)smem;
;     for (int i = tid; i < 8 * 15 * 31; i += 512) rpb_s[i] = P.in[I_RPB][i];
;     __syncthreads();
; __global__ __launch_bounds__(512, 2) void mega(Params P) {
;     ...
;         PH(2) { REP(1) phase_na(P, shm); REP(2) phase_lru<1>(P, shm); SYNC(2); }
.LBB0_203:
	s_setprio 0
	s_add_u32 s40, s90, 0x16000000
	s_addc_u32 s41, s91, 0
	s_cmp_lt_i32 s92, 3
	s_cselect_b64 s[0:1], -1, 0
	s_cmp_gt_i32 s93, 2
	s_cselect_b64 s[4:5], -1, 0
	s_and_b64 s[0:1], s[0:1], s[4:5]
	s_andn2_b64 vcc, exec, s[0:1]
	s_cbranch_vccnz .LBB0_434
	s_mov_b32 s98, 0
	s_bitcmp1_b32 s2, 3
	s_cbranch_scc0 .Lna_start
	s_mov_b32 s98, 1
	s_and_b32 s3, s2, 7
	s_lshl_b32 s24, s3, 7
	v_bfe_u32 v65, v144, 4, 2
	v_and_b32_e32 v64, 15, v144
	v_lshlrev_b32_e32 v68, 3, v65
	v_lshlrev_b32_e32 v69, 2, v65
	v_lshlrev_b32_e32 v66, 4, v65
	v_mov_b32_e32 v67, 0
	v_mov_b32_e32 v71, 0
	s_mov_b64 s[4:5], 0
	s_branch .LBB0_338
.Lna_start:
	v_lshlrev_b32_e32 v2, 2, v144
	v_mov_b32_e32 v3, 0
	v_lshl_add_u64 v[0:1], s[64:65], 0, v[2:3]
	v_add_co_u32_e32 v4, vcc, 0x1000, v0
	v_or_b32_e32 v3, 0x1000, v2
	s_nop 0
	v_addc_co_u32_e32 v5, vcc, 0, v1, vcc
	v_add_co_u32_e32 v6, vcc, 0x2000, v0
	v_or_b32_e32 v8, 0x2000, v2
	s_nop 0
	v_addc_co_u32_e32 v7, vcc, 0, v1, vcc
	global_load_dword v9, v2, s[64:65]
	global_load_dword v10, v2, s[64:65] offset:2048
	global_load_dword v11, v3, s[64:65]
	global_load_dword v12, v[4:5], off offset:2048
	global_load_dword v13, v8, s[64:65]
	s_waitcnt lgkmcnt(0)
	global_load_dword v14, v[6:7], off offset:2048
	s_movk_i32 s0, 0x288
	v_add_u32_e32 v2, 0, v2
	v_cmp_gt_u32_e32 vcc, s0, v144
	s_waitcnt vmcnt(4)
	ds_write2st64_b32 v2, v9, v10 offset1:8
	s_waitcnt vmcnt(2)
	ds_write2st64_b32 v2, v11, v12 offset0:16 offset1:24
	s_waitcnt vmcnt(0)
	ds_write2st64_b32 v2, v13, v14 offset0:32 offset1:40
	s_and_saveexec_b64 s[0:1], vcc
	s_cbranch_execz .LBB0_207
	v_or_b32_e32 v3, 0xc00, v144
	v_lshlrev_b32_e32 v4, 2, v3
	global_load_dword v4, v4, s[64:65]
	s_movk_i32 s3, 0xc88
	v_cmp_gt_u32_e32 vcc, s3, v3
	s_waitcnt vmcnt(0)
	ds_write_b32 v2, v4 offset:12288
	s_and_saveexec_b64 s[4:5], vcc
	s_xor_b64 s[4:5], exec, s[4:5]
	s_cbranch_execz .LBB0_207
	v_add_co_u32_e32 v0, vcc, 0x3000, v0
	s_nop 1
	v_addc_co_u32_e32 v1, vcc, 0, v1, vcc
	global_load_dword v0, v[0:1], off offset:2048
	s_waitcnt vmcnt(0)
	ds_write_b32 v2, v0 offset:14336

; template <int PASS> __device__ void phase_lru(const Params& P, unsigned char* smem) {
;     const int tid = threadIdx.x, lane = tid & 63, wid = tid >> 6, l15 = lane & 15, l4 = lane >> 4;
;     bf16_t* xcb = (bf16_t*)smem;
;     float2* au = (float2*)(smem + 34816);
;     bf16_t* hbuf = (bf16_t*)(smem + 100352);
;     bf16_t* sumt = (bf16_t*)(smem + 133120);
;     const bf16_t* XR = (const bf16_t*)((const unsigned char*)P.out + 64 * MiB);
;     const bf16_t* GR = (const bf16_t*)(P.ws + O_R2 + 64 * MiB);
;     bf16_t* YR = (bf16_t*)(P.ws + O_R3 + 64 * MiB);
;     const bf16_t* LW = (const bf16_t*)(P.ws + O_LRUW);
;     float2* LSUM = (float2*)(P.ws + O_LSUM);
;     constexpr int NT = (PASS == 2) ? 2 : 1;
;     const int ctt = tid >> 4, cc8 = (tid & 15) * 8;
;     const int gdir = wid >> 2, gc0 = (wid & 3) * 32;
;     const int sdir = tid >> 7, sc_ = tid & 127;
;     const int nloc = (2048 - (int)blockIdx.x + (int)gridDim.x - 1) / (int)gridDim.x;
;     if (nloc <= 0) return;
;     float cw[4][8], cb[8];
;     uint4 xr[NT][4];
;     ...
;     LruUnit U = lru_decode((int)blockIdx.x);
;     LRU_LOADW(U); LRU_LOADX(U, 0); LRU_CONV(0);
.LBB0_338:
	s_or_b64 exec, exec, s[4:5]
	s_cmp_eq_u32 s98, 2
	s_cbranch_scc1 .Lsw_done
	s_abs_i32 s0, s94
	v_cvt_f32_u32_e32 v0, s0
	s_sub_i32 s1, s94, s2
	s_add_i32 s4, s1, 0x7ff
	s_sub_i32 s1, 0xfffff801, s1
	v_rcp_iflag_f32_e32 v0, v0
	s_xor_b32 s6, s4, s94
	s_sub_i32 s5, 0, s0
	s_max_i32 s1, s4, s1
	v_mul_f32_e32 v0, 0x4f7ffffe, v0
	v_cvt_u32_f32_e32 v0, v0
	s_ashr_i32 s4, s6, 31
	v_lshrrev_b32_e32 v135, 4, v144
	v_readfirstlane_b32 s6, v0
	s_mul_i32 s5, s5, s6
	s_mul_hi_u32 s5, s6, s5
	s_add_i32 s6, s6, s5
	s_mul_hi_u32 s5, s1, s6
	s_mul_i32 s6, s5, s0
	s_sub_i32 s1, s1, s6
	s_add_i32 s6, s5, 1
	s_sub_i32 s7, s1, s0
	s_cmp_ge_u32 s1, s0
	s_cselect_b32 s5, s6, s5
	s_cselect_b32 s1, s7, s1
	s_add_i32 s6, s5, 1
	s_cmp_ge_u32 s1, s0
	s_cselect_b32 s0, s6, s5
	s_xor_b32 s0, s0, s4
	s_sub_i32 s6, s0, s4
	s_cmp_lt_i32 s6, 1
	s_barrier
	s_cbranch_scc1 .LBB0_380
	s_add_u32 s4, s88, 0x4000000
	s_addc_u32 s5, s89, 0
	s_ashr_i32 s8, s2, 3
	s_and_b32 s0, s8, 0x7fffffe0
	s_cmpk_lt_i32 s8, 0x80
	s_cselect_b32 s0, 0, s0
	s_cselect_b32 s1, 0x80, 32
	s_add_i32 s1, s0, s1
	s_lshl_b32 s7, s8, 7
	v_add_u32_e32 v145, -2, v135
	s_lshl_b32 s19, s0, 7
	s_lshl_b32 s21, s1, 7
	v_add_u32_e32 v52, s7, v145
	s_lshl_b32 s0, s24, 1
	s_add_u32 s10, s4, s0
	v_cmp_le_i32_e32 vcc, s19, v52
	v_cmp_gt_i32_e64 s[0:1], s21, v52
	v_lshlrev_b32_e32 v0, 3, v144
	s_addc_u32 s11, s5, 0
	s_and_b64 s[12:13], vcc, s[0:1]
	s_lshl_b32 s9, s24, 2
	v_and_b32_e32 v67, 0x78, v0
	v_mov_b32_e32 v42, 0
	s_add_u32 s0, s66, s9
	s_addc_u32 s1, s67, 0
	v_lshlrev_b32_e32 v56, 2, v67
	v_mov_b32_e32 v57, v42
	v_lshl_add_u64 v[24:25], s[0:1], 0, v[56:57]
	s_mov_b64 s[14:15], 0x3000
	v_readlane_b32 s68, v248, 6
	v_lshl_add_u64 v[36:37], v[24:25], 0, s[14:15]
	s_mov_b64 s[14:15], 0x2000
	v_readlane_b32 s69, v248, 7
	v_lshl_add_u64 v[28:29], v[24:25], 0, s[14:15]
	s_mov_b64 s[14:15], 0x1000
	s_mov_b64 s[60:61], s[68:69]
	v_lshl_add_u64 v[20:21], v[24:25], 0, s[14:15]
	s_add_u32 s14, s60, s9
	s_addc_u32 s15, s61, 0
	global_load_dwordx4 v[4:7], v56, s[14:15] offset:16
	global_load_dwordx4 v[0:3], v56, s[14:15]
	global_load_dwordx4 v[12:15], v56, s[0:1] offset:16
	global_load_dwordx4 v[8:11], v56, s[0:1]
	s_movk_i32 s0, 0x1000
	v_add_co_u32_e32 v16, vcc, s0, v24
	v_lshlrev_b32_e32 v58, 1, v67
	s_nop 0
	v_addc_co_u32_e32 v17, vcc, 0, v25, vcc
	v_add_co_u32_e32 v26, vcc, 0x2000, v24
	global_load_dwordx4 v[16:19], v[16:17], off
	s_nop 0
	global_load_dwordx4 v[20:23], v[20:21], off offset:16
	v_addc_co_u32_e32 v27, vcc, 0, v25, vcc
	v_add_co_u32_e32 v30, vcc, 0x3000, v24
	v_mov_b32_e32 v59, v42
	s_nop 0
	v_addc_co_u32_e32 v31, vcc, 0, v25, vcc
	global_load_dwordx4 v[24:27], v[26:27], off
	s_nop 0
	global_load_dwordx4 v[32:35], v[30:31], off
	s_nop 0
	global_load_dwordx4 v[28:31], v[28:29], off offset:16
	s_nop 0
	global_load_dwordx4 v[36:39], v[36:37], off offset:16
	v_mov_b32_e32 v43, v42
	v_lshl_add_u64 v[60:61], s[10:11], 0, v[58:59]
	v_mov_b64_e32 v[46:47], v[42:43]
	v_mov_b64_e32 v[44:45], v[42:43]
	v_readlane_b32 s70, v248, 8
	v_readlane_b32 s71, v248, 9
	v_readlane_b32 s72, v248, 10
	v_readlane_b32 s73, v248, 11
	v_readlane_b32 s74, v248, 12
	v_readlane_b32 s75, v248, 13
	v_readlane_b32 s76, v248, 14
	v_readlane_b32 s77, v248, 15
	v_readlane_b32 s78, v248, 16
	v_readlane_b32 s79, v248, 17
	v_readlane_b32 s80, v248, 18
	v_readlane_b32 s81, v248, 19
	v_readlane_b32 s82, v248, 20
	v_readlane_b32 s83, v248, 21
	s_and_saveexec_b64 s[0:1], s[12:13]
	s_cbranch_execz .LBB0_341
	v_mov_b32_e32 v53, v42
	v_lshlrev_b64 v[40:41], 11, v[52:53]
	v_lshl_add_u64 v[40:41], v[60:61], 0, v[40:41]
	global_load_dwordx4 v[44:47], v[40:41], off

; #define PH(k) if (((PHMASK >> (k)) & 1) && P.ph_lo <= (k) && (k) < P.ph_hi)
; #define SYNC(k) do { if ((k) + 1 < P.ph_hi) { if ((k) == 0) grid.sync(); else xcd_barrier(xb); } } while (0)
; #define REP(b) for (int _rep = 0; _rep < (((REPMASK >> (b)) & 1) ? 2 : 1); ++_rep)
; __global__ __launch_bounds__(512, 2) void mega(Params P) {
;     ...
;         PH(2) { REP(1) phase_na(P, shm); REP(2) phase_lru<1>(P, shm); SYNC(2); }
.LBB0_380:
	s_cmp_eq_u32 s98, 1
	s_cbranch_scc0 .Lsw_done
	s_mov_b32 s98, 2
	s_waitcnt lgkmcnt(0)
	s_barrier
	s_branch .Lna_start
